# v45 without the three hazard s_nop pads per tile: the next chunk's first exp (or add) slides behind the cvts to supply the VALU->MFMA wait states
# speedup vs baseline: 1.0006x; 1.0006x over previous
; DI void attn_item(const P& p, int l, int item, char* smem) {
;     ...
;   for (int kt = -1; kt < 128; ++kt) {
;     if (kt + 1 < 128) {
;       u16* Kd = Ks + ((kt + 1) & 1) * (256 * 72);
;       u16* Vd = Kd + 2 * 64 * 72;
; #pragma unroll
;       for (int i = 0; i < 2; ++i) {
;         const int row = tid >> 3, kc = tid & 7;
;         *(u32x4*)(Kd + (i * 64 + row) * 72 + kc * 8) = kreg[i];
;       }
; #pragma unroll
;       for (int i = 0; i < 2; ++i) {
;         const int cid = tid + NT * i;
;         const int e = cid >> 3, kc = cid & 7;
;         uint2 w0; w0.x = vreg[i][0]; w0.y = vreg[i][1];
;         uint2 w1; w1.x = vreg[i][2]; w1.y = vreg[i][3];
;         u16* vd = Vd + e * 72 + (kc >> 1) * 16 + (kc & 1) * 4;
;         *(uint2*)vd = w0;
;         *(uint2*)(vd + 8) = w1;
;       }
;     }
;     if (kt + 2 < 128) {
;       const int kn = kt + 2;
; #pragma unroll
;       for (int i = 0; i < 2; ++i) kreg[i] = *(const u32x4*)(kbase + ((size_t)i * SEQ + kn * 64) * 64 + tid * 8);
; #pragma unroll
;       for (int i = 0; i < 2; ++i) {
;         const int cid = tid + NT * i;
;         const int e = cid >> 3, kc = cid & 7;
;         vreg[i] = *(const u32x4*)(vbase + (size_t)e * VTP + kn * 64 + kc * 8);
;       }
;     }
;     __builtin_amdgcn_sched_barrier(0x38F);
;     if (kt >= 0) {
;       const u16* Kc = Ks + (kt & 1) * (256 * 72);
;       const u16* Vc = Kc + 2 * 64 * 72;
;       bf16x8 kf[8];
; #pragma unroll
;       for (int i = 0; i < 8; ++i)
;         kf[i] = *(const bf16x8*)(Kc + (c * 64 + 32 * (i & 1) + li) * 72 + 16 * (i >> 1) + 8 * g);
;       u32x4 vf[16];
; #pragma unroll
;       for (int i = 0; i < 16; ++i) {
;         const int eb = i & 3, s = (i >> 2) & 1, kb = i >> 3;
;         vf[i] = *(const u32x4*)(Vc + (32 * eb + li) * 72 + 32 * kb + 16 * s + 8 * g);
;       }
;       f32x16 S[2];
; #pragma unroll
;       for (int kb = 0; kb < 2; ++kb)
; #pragma unroll
;         for (int r = 0; r < 16; ++r) S[kb][r] = negm;
; #pragma unroll
;       for (int i = 0; i < 8; ++i) S[i & 1] = MFMA(kf[i], qf[i >> 1], S[i & 1]);
;       u32x4 pk[4];
;       float sum = 0.f;
; #pragma unroll
;       for (int ch = 0; ch < 4; ++ch) {
;         const int kb = ch >> 1, s = ch & 1;
; #pragma unroll
;         for (int j2 = 0; j2 < 4; ++j2) {
;           const float p0 = __builtin_amdgcn_exp2f(S[kb][8 * s + 2 * j2]);
.Lat_loop:
	s_waitcnt lgkmcnt(4)
	v_mfma_f32_32x32x16_bf16 v[64:79], v[136:139], v[176:179], v[64:79]
	ds_read_b128 v[136:139], v151 offset:9248
	v_exp_f32_e64 v104, v104
	v_exp_f32_e32 v105, v105
	v_mfma_f32_32x32x16_bf16 v[48:63], v[152:155], v[176:179], v[48:63]
	ds_read_b128 v[152:155], v151 offset:13856
	v_exp_f32_e64 v106, v106
	v_exp_f32_e32 v107, v107
	v_cvt_pk_bf16_f32 v180, v104, v105
	s_waitcnt lgkmcnt(4)
	v_mfma_f32_32x32x16_bf16 v[32:47], v[224:227], v[176:179], v[32:47]
	ds_read_b128 v[224:227], v151 offset:64
	v_exp_f32_e32 v108, v108
	v_exp_f32_e32 v109, v109
	v_cvt_pk_bf16_f32 v181, v106, v107
	v_mfma_f32_32x32x16_bf16 v[0:15], v[244:247], v[176:179], v[0:15]
	ds_read_b128 v[244:247], v151 offset:4672
	v_exp_f32_e32 v110, v110
	v_exp_f32_e32 v111, v111
	v_cvt_pk_bf16_f32 v182, v108, v109
	v_cvt_pk_bf16_f32 v183, v110, v111
	v_exp_f32_e32 v80, v80
	s_waitcnt lgkmcnt(4)
	v_mfma_f32_32x32x16_bf16 v[64:79], v[128:131], v[180:183], v[64:79]
	ds_read_b128 v[128:131], v151 offset:9280
	v_exp_f32_e64 v81, v81
	v_mfma_f32_32x32x16_bf16 v[48:63], v[132:135], v[180:183], v[48:63]
	ds_read_b128 v[132:135], v151 offset:13888
	v_exp_f32_e64 v82, v82
	v_exp_f32_e32 v83, v83
	v_cvt_pk_bf16_f32 v184, v80, v81
	s_waitcnt lgkmcnt(4)
	v_mfma_f32_32x32x16_bf16 v[32:47], v[136:139], v[180:183], v[32:47]
	ds_read_b128 v[136:139], v151 offset:96
	v_exp_f32_e32 v84, v84
	v_exp_f32_e32 v85, v85
	v_cvt_pk_bf16_f32 v185, v82, v83
	v_mfma_f32_32x32x16_bf16 v[0:15], v[152:155], v[180:183], v[0:15]
	ds_read_b128 v[152:155], v151 offset:4704
	v_exp_f32_e32 v86, v86
	v_exp_f32_e32 v87, v87
	v_cvt_pk_bf16_f32 v186, v84, v85
	v_cvt_pk_bf16_f32 v187, v86, v87
	v_exp_f32_e32 v88, v88
	s_waitcnt lgkmcnt(4)
	v_mfma_f32_32x32x16_bf16 v[64:79], v[224:227], v[184:187], v[64:79]
	ds_read_b128 v[224:227], v151 offset:9312
	v_exp_f32_e64 v89, v89
	v_mfma_f32_32x32x16_bf16 v[48:63], v[244:247], v[184:187], v[48:63]
	ds_read_b128 v[244:247], v151 offset:13920
	v_exp_f32_e64 v90, v90
	v_exp_f32_e32 v91, v91
	v_cvt_pk_bf16_f32 v192, v88, v89
	s_waitcnt lgkmcnt(4)
	v_mfma_f32_32x32x16_bf16 v[32:47], v[128:131], v[184:187], v[32:47]
	v_exp_f32_e64 v92, v92
	v_exp_f32_e32 v93, v93
	v_cvt_pk_bf16_f32 v193, v90, v91
	s_waitcnt vmcnt(0)
	ds_write_b128 v168, v[228:231] offset:36864
	ds_write_b128 v168, v[232:235] offset:46080
	v_mfma_f32_32x32x16_bf16 v[0:15], v[132:135], v[184:187], v[0:15]
	v_exp_f32_e32 v94, v94
	v_exp_f32_e32 v95, v95
	v_cvt_pk_bf16_f32 v194, v92, v93
	v_cvt_pk_bf16_f32 v195, v94, v95
	v_add_f32_e64 v167, v167, v104
	ds_write_b64 v169, v[236:237] offset:55296
	ds_write_b64 v169, v[238:239] offset:55312
	s_waitcnt lgkmcnt(6)
	v_mfma_f32_32x32x16_bf16 v[64:79], v[136:139], v[192:195], v[64:79]
	v_add_f32_e32 v190, v190, v105
	v_add_f32_e32 v191, v191, v106
	v_add_f32_e32 v196, v196, v107
	ds_write_b64 v143, v[240:241] offset:55296
	ds_write_b64 v143, v[242:243] offset:55312
	v_mfma_f32_32x32x16_bf16 v[48:63], v[152:155], v[192:195], v[48:63]
	v_add_f32_e32 v167, v167, v108
	v_add_f32_e32 v190, v190, v109
	v_add_f32_e64 v191, v191, v110
	v_add_f32_e32 v196, v196, v111
	s_waitcnt lgkmcnt(6)
	v_mfma_f32_32x32x16_bf16 v[32:47], v[224:227], v[192:195], v[32:47]
	v_add_f32_e32 v167, v167, v80
	v_add_f32_e32 v190, v190, v81
	v_add_f32_e32 v191, v191, v82
	v_add_f32_e32 v196, v196, v83
	v_mfma_f32_32x32x16_bf16 v[0:15], v[244:247], v[192:195], v[0:15]
	v_add_f32_e32 v167, v167, v84
	v_add_f32_e32 v190, v190, v85
	v_add_f32_e32 v191, v191, v86
	v_add_f32_e32 v196, v196, v87
	s_waitcnt lgkmcnt(0)
	s_barrier
	ds_read_b128 v[128:131], v150 offset:36864
	ds_read_b128 v[132:135], v150 offset:36896
	ds_read_b128 v[136:139], v150 offset:36928
	ds_read_b128 v[152:155], v150 offset:36960
	ds_read_b128 v[224:227], v150 offset:41472
	ds_read_b128 v[244:247], v150 offset:41504
	global_load_dwordx4 v[232:235], v148, s[98:99]
	global_load_dwordx4 v[228:231], v156, s[98:99]
	global_load_dwordx4 v[236:239], v146, s[100:101]
	global_load_dwordx4 v[240:243], v144, s[100:101]
	s_waitcnt lgkmcnt(4)
	v_mfma_f32_32x32x16_bf16 v[96:111], v[128:131], v[112:115], v[16:31]
	ds_read_b128 v[128:131], v150 offset:41536
	v_add_f32_e64 v167, v167, v88
	v_add_f32_e32 v190, v190, v89
	v_mfma_f32_32x32x16_bf16 v[96:111], v[132:135], v[116:119], v[96:111]
	ds_read_b128 v[132:135], v150 offset:41568
	v_add_f32_e64 v191, v191, v90
	v_add_f32_e32 v196, v196, v91
	s_waitcnt lgkmcnt(4)
	v_mfma_f32_32x32x16_bf16 v[96:111], v[136:139], v[124:127], v[96:111]
	ds_read_b128 v[136:139], v151 offset:36864
	v_add_f32_e32 v167, v167, v92
	v_add_f32_e32 v190, v190, v93
	v_mfma_f32_32x32x16_bf16 v[96:111], v[152:155], v[120:123], v[96:111]
	ds_read_b128 v[152:155], v151 offset:41472
	v_add_f32_e64 v191, v191, v94
	v_add_f32_e32 v196, v196, v95
	s_add_u32 s98, s98, s14
	s_addc_u32 s99, s99, s15
	s_waitcnt lgkmcnt(4)
	v_mfma_f32_32x32x16_bf16 v[80:95], v[224:227], v[112:115], v[16:31]
	ds_read_b128 v[224:227], v151 offset:46080
	s_add_u32 s100, s100, s58
	s_addc_u32 s101, s101, s59
	v_mfma_f32_32x32x16_bf16 v[80:95], v[244:247], v[116:119], v[80:95]
	ds_read_b128 v[244:247], v151 offset:50688
	s_nop 2
	v_exp_f32_e32 v96, v96
	v_exp_f32_e32 v97, v97
	s_waitcnt lgkmcnt(4)
	v_mfma_f32_32x32x16_bf16 v[80:95], v[128:131], v[124:127], v[80:95]
	ds_read_b128 v[128:131], v151 offset:36896
	v_exp_f32_e32 v98, v98
	v_exp_f32_e32 v99, v99
	v_exp_f32_e64 v100, v100
	v_mfma_f32_32x32x16_bf16 v[80:95], v[132:135], v[120:123], v[80:95]
	ds_read_b128 v[132:135], v151 offset:41504
	v_exp_f32_e32 v101, v101
	v_exp_f32_e32 v102, v102
	v_exp_f32_e32 v103, v103
	v_add_f32_e32 v167, v167, v96
	v_add_f32_e32 v190, v190, v97
	v_add_f32_e32 v191, v191, v98
	v_cvt_pk_bf16_f32 v176, v96, v97
	v_cvt_pk_bf16_f32 v177, v98, v99
	v_cvt_pk_bf16_f32 v178, v100, v101
	v_cvt_pk_bf16_f32 v179, v102, v103
	v_add_f32_e32 v196, v196, v99
	v_add_f32_e32 v167, v167, v100
	v_add_f32_e32 v190, v190, v101
	v_add_f32_e32 v191, v191, v102
	v_add_f32_e32 v196, v196, v103
	s_waitcnt lgkmcnt(4)
; DI void attn_item(const P& p, int l, int item, char* smem) {
;     ...
;   for (int kt = -1; kt < 128; ++kt) {
;     if (kt + 1 < 128) {
;       u16* Kd = Ks + ((kt + 1) & 1) * (256 * 72);
;       u16* Vd = Kd + 2 * 64 * 72;
; #pragma unroll
;       for (int i = 0; i < 2; ++i) {
;         const int row = tid >> 3, kc = tid & 7;
;         *(u32x4*)(Kd + (i * 64 + row) * 72 + kc * 8) = kreg[i];
;       }
; #pragma unroll
;       for (int i = 0; i < 2; ++i) {
;         const int cid = tid + NT * i;
;         const int e = cid >> 3, kc = cid & 7;
;         uint2 w0; w0.x = vreg[i][0]; w0.y = vreg[i][1];
;         uint2 w1; w1.x = vreg[i][2]; w1.y = vreg[i][3];
;         u16* vd = Vd + e * 72 + (kc >> 1) * 16 + (kc & 1) * 4;
;         *(uint2*)vd = w0;
;         *(uint2*)(vd + 8) = w1;
;       }
;     }
;     if (kt + 2 < 128) {
;       const int kn = kt + 2;
; #pragma unroll
;       for (int i = 0; i < 2; ++i) kreg[i] = *(const u32x4*)(kbase + ((size_t)i * SEQ + kn * 64) * 64 + tid * 8);
; #pragma unroll
;       for (int i = 0; i < 2; ++i) {
;         const int cid = tid + NT * i;
;         const int e = cid >> 3, kc = cid & 7;
;         vreg[i] = *(const u32x4*)(vbase + (size_t)e * VTP + kn * 64 + kc * 8);
;       }
;     }
;     __builtin_amdgcn_sched_barrier(0x38F);
;     if (kt >= 0) {
;       const u16* Kc = Ks + (kt & 1) * (256 * 72);
;       const u16* Vc = Kc + 2 * 64 * 72;
;       bf16x8 kf[8];
; #pragma unroll
;       for (int i = 0; i < 8; ++i)
;         kf[i] = *(const bf16x8*)(Kc + (c * 64 + 32 * (i & 1) + li) * 72 + 16 * (i >> 1) + 8 * g);
;       u32x4 vf[16];
; #pragma unroll
;       for (int i = 0; i < 16; ++i) {
;         const int eb = i & 3, s = (i >> 2) & 1, kb = i >> 3;
;         vf[i] = *(const u32x4*)(Vc + (32 * eb + li) * 72 + 32 * kb + 16 * s + 8 * g);
;       }
;       f32x16 S[2];
; #pragma unroll
;       for (int kb = 0; kb < 2; ++kb)
; #pragma unroll
;         for (int r = 0; r < 16; ++r) S[kb][r] = negm;
; #pragma unroll
;       for (int i = 0; i < 8; ++i) S[i & 1] = MFMA(kf[i], qf[i >> 1], S[i & 1]);
;       u32x4 pk[4];
;       float sum = 0.f;
; #pragma unroll
;       for (int ch = 0; ch < 4; ++ch) {
;         const int kb = ch >> 1, s = ch & 1;
; #pragma unroll
;         for (int j2 = 0; j2 < 4; ++j2) {
;           const float p0 = __builtin_amdgcn_exp2f(S[kb][8 * s + 2 * j2]);
	v_mfma_f32_32x32x16_bf16 v[64:79], v[136:139], v[176:179], v[64:79]
	ds_read_b128 v[136:139], v151 offset:46112
	v_exp_f32_e32 v104, v104
	v_exp_f32_e32 v105, v105
	v_mfma_f32_32x32x16_bf16 v[48:63], v[152:155], v[176:179], v[48:63]
	ds_read_b128 v[152:155], v151 offset:50720
	v_exp_f32_e64 v106, v106
	v_exp_f32_e32 v107, v107
	v_cvt_pk_bf16_f32 v180, v104, v105
	s_waitcnt lgkmcnt(4)
	v_mfma_f32_32x32x16_bf16 v[32:47], v[224:227], v[176:179], v[32:47]
	ds_read_b128 v[224:227], v151 offset:36928
	v_exp_f32_e32 v108, v108
	v_exp_f32_e32 v109, v109
	v_cvt_pk_bf16_f32 v181, v106, v107
	v_mfma_f32_32x32x16_bf16 v[0:15], v[244:247], v[176:179], v[0:15]
	ds_read_b128 v[244:247], v151 offset:41536
	v_exp_f32_e32 v110, v110
	v_exp_f32_e32 v111, v111
	v_cvt_pk_bf16_f32 v182, v108, v109
	v_cvt_pk_bf16_f32 v183, v110, v111
	v_exp_f32_e32 v80, v80
	s_waitcnt lgkmcnt(4)
	v_mfma_f32_32x32x16_bf16 v[64:79], v[128:131], v[180:183], v[64:79]
	ds_read_b128 v[128:131], v151 offset:46144
	v_exp_f32_e64 v81, v81
	v_mfma_f32_32x32x16_bf16 v[48:63], v[132:135], v[180:183], v[48:63]
	ds_read_b128 v[132:135], v151 offset:50752
	v_exp_f32_e64 v82, v82
	v_exp_f32_e32 v83, v83
	v_cvt_pk_bf16_f32 v184, v80, v81
	s_waitcnt lgkmcnt(4)
	v_mfma_f32_32x32x16_bf16 v[32:47], v[136:139], v[180:183], v[32:47]
	ds_read_b128 v[136:139], v151 offset:36960
	v_exp_f32_e32 v84, v84
	v_exp_f32_e32 v85, v85
	v_cvt_pk_bf16_f32 v185, v82, v83
	v_mfma_f32_32x32x16_bf16 v[0:15], v[152:155], v[180:183], v[0:15]
	ds_read_b128 v[152:155], v151 offset:41568
	v_exp_f32_e32 v86, v86
	v_exp_f32_e32 v87, v87
	v_cvt_pk_bf16_f32 v186, v84, v85
	v_cvt_pk_bf16_f32 v187, v86, v87
	v_exp_f32_e32 v88, v88
	s_waitcnt lgkmcnt(4)
	v_mfma_f32_32x32x16_bf16 v[64:79], v[224:227], v[184:187], v[64:79]
	ds_read_b128 v[224:227], v151 offset:46176
	v_exp_f32_e64 v89, v89
	v_mfma_f32_32x32x16_bf16 v[48:63], v[244:247], v[184:187], v[48:63]
	ds_read_b128 v[244:247], v151 offset:50784
	v_exp_f32_e64 v90, v90
	v_exp_f32_e32 v91, v91
	v_cvt_pk_bf16_f32 v192, v88, v89
	s_waitcnt lgkmcnt(4)
	v_mfma_f32_32x32x16_bf16 v[32:47], v[128:131], v[184:187], v[32:47]
	v_exp_f32_e64 v92, v92
	v_exp_f32_e32 v93, v93
	v_cvt_pk_bf16_f32 v193, v90, v91
	s_waitcnt vmcnt(0)
	ds_write_b128 v168, v[228:231] offset:0
	ds_write_b128 v168, v[232:235] offset:9216
	v_mfma_f32_32x32x16_bf16 v[0:15], v[132:135], v[184:187], v[0:15]
	v_exp_f32_e32 v94, v94
	v_exp_f32_e32 v95, v95
	v_cvt_pk_bf16_f32 v194, v92, v93
	v_cvt_pk_bf16_f32 v195, v94, v95
	v_add_f32_e64 v167, v167, v104
	ds_write_b64 v169, v[236:237] offset:18432
	ds_write_b64 v169, v[238:239] offset:18448
	s_waitcnt lgkmcnt(6)
	v_mfma_f32_32x32x16_bf16 v[64:79], v[136:139], v[192:195], v[64:79]
	v_add_f32_e32 v190, v190, v105
	v_add_f32_e32 v191, v191, v106
	v_add_f32_e32 v196, v196, v107
	ds_write_b64 v143, v[240:241] offset:18432
	ds_write_b64 v143, v[242:243] offset:18448
	v_mfma_f32_32x32x16_bf16 v[48:63], v[152:155], v[192:195], v[48:63]
	v_add_f32_e32 v167, v167, v108
	v_add_f32_e32 v190, v190, v109
	v_add_f32_e64 v191, v191, v110
	v_add_f32_e32 v196, v196, v111
	s_waitcnt lgkmcnt(6)
	v_mfma_f32_32x32x16_bf16 v[32:47], v[224:227], v[192:195], v[32:47]
	v_add_f32_e32 v167, v167, v80
	v_add_f32_e32 v190, v190, v81
	v_add_f32_e32 v191, v191, v82
	v_add_f32_e32 v196, v196, v83
	v_mfma_f32_32x32x16_bf16 v[0:15], v[244:247], v[192:195], v[0:15]
	v_add_f32_e32 v167, v167, v84
	v_add_f32_e32 v190, v190, v85
	v_add_f32_e64 v191, v191, v86
	v_add_f32_e32 v196, v196, v87
	s_waitcnt lgkmcnt(0)
	s_barrier
	s_add_i32 s10, s10, -1
	s_cmp_eq_u32 s10, 0
	s_cbranch_scc1 .Lat_exit
	ds_read_b128 v[128:131], v150 offset:0
	ds_read_b128 v[132:135], v150 offset:32
	ds_read_b128 v[136:139], v150 offset:64
	ds_read_b128 v[152:155], v150 offset:96
	ds_read_b128 v[224:227], v150 offset:4608
	ds_read_b128 v[244:247], v150 offset:4640
	global_load_dwordx4 v[232:235], v148, s[98:99]
	global_load_dwordx4 v[228:231], v156, s[98:99]
	global_load_dwordx4 v[236:239], v146, s[100:101]
	global_load_dwordx4 v[240:243], v144, s[100:101]
	s_waitcnt lgkmcnt(4)
	v_mfma_f32_32x32x16_bf16 v[96:111], v[128:131], v[112:115], v[16:31]
	ds_read_b128 v[128:131], v150 offset:4672
	v_add_f32_e64 v167, v167, v88
	v_add_f32_e32 v190, v190, v89
	v_mfma_f32_32x32x16_bf16 v[96:111], v[132:135], v[116:119], v[96:111]
	ds_read_b128 v[132:135], v150 offset:4704
	v_add_f32_e64 v191, v191, v90
	v_add_f32_e32 v196, v196, v91
	s_waitcnt lgkmcnt(4)
	v_mfma_f32_32x32x16_bf16 v[96:111], v[136:139], v[124:127], v[96:111]
	ds_read_b128 v[136:139], v151 offset:0
	v_add_f32_e32 v167, v167, v92
	v_add_f32_e32 v190, v190, v93
	v_mfma_f32_32x32x16_bf16 v[96:111], v[152:155], v[120:123], v[96:111]
	ds_read_b128 v[152:155], v151 offset:4608
	v_add_f32_e64 v191, v191, v94
	v_add_f32_e32 v196, v196, v95
	s_add_u32 s98, s98, s14
	s_addc_u32 s99, s99, s15
	s_waitcnt lgkmcnt(4)
	v_mfma_f32_32x32x16_bf16 v[80:95], v[224:227], v[112:115], v[16:31]
	ds_read_b128 v[224:227], v151 offset:9216
	s_add_u32 s100, s100, s58
	s_addc_u32 s101, s101, s59
	v_mfma_f32_32x32x16_bf16 v[80:95], v[244:247], v[116:119], v[80:95]
	ds_read_b128 v[244:247], v151 offset:13824
	s_nop 2
	v_exp_f32_e32 v96, v96
	v_exp_f32_e32 v97, v97
	s_waitcnt lgkmcnt(4)
	v_mfma_f32_32x32x16_bf16 v[80:95], v[128:131], v[124:127], v[80:95]
	ds_read_b128 v[128:131], v151 offset:32
	v_exp_f32_e32 v98, v98
	v_exp_f32_e32 v99, v99
	v_exp_f32_e64 v100, v100
	v_mfma_f32_32x32x16_bf16 v[80:95], v[132:135], v[120:123], v[80:95]
	ds_read_b128 v[132:135], v151 offset:4640
	v_exp_f32_e32 v101, v101
	v_exp_f32_e32 v102, v102
	v_exp_f32_e32 v103, v103
	v_add_f32_e32 v167, v167, v96
	v_add_f32_e32 v190, v190, v97
	v_add_f32_e32 v191, v191, v98
	v_cvt_pk_bf16_f32 v176, v96, v97
	v_cvt_pk_bf16_f32 v177, v98, v99
	v_cvt_pk_bf16_f32 v178, v100, v101
	v_cvt_pk_bf16_f32 v179, v102, v103
	v_add_f32_e32 v196, v196, v99
	v_add_f32_e32 v167, v167, v100
	v_add_f32_e32 v190, v190, v101
	v_add_f32_e32 v191, v191, v102
	v_add_f32_e64 v196, v196, v103
	s_branch .Lat_loop
; DI void attn_item(const P& p, int l, int item, char* smem) {
;     ...
;   for (int kt = -1; kt < 128; ++kt) {
;     if (kt + 1 < 128) {
;       u16* Kd = Ks + ((kt + 1) & 1) * (256 * 72);
;       u16* Vd = Kd + 2 * 64 * 72;
; #pragma unroll
;       for (int i = 0; i < 2; ++i) {
;         const int row = tid >> 3, kc = tid & 7;
;         *(u32x4*)(Kd + (i * 64 + row) * 72 + kc * 8) = kreg[i];
;       }
; #pragma unroll
;       for (int i = 0; i < 2; ++i) {
;         const int cid = tid + NT * i;
;         const int e = cid >> 3, kc = cid & 7;
;         uint2 w0; w0.x = vreg[i][0]; w0.y = vreg[i][1];
;         uint2 w1; w1.x = vreg[i][2]; w1.y = vreg[i][3];
;         u16* vd = Vd + e * 72 + (kc >> 1) * 16 + (kc & 1) * 4;
;         *(uint2*)vd = w0;
;         *(uint2*)(vd + 8) = w1;
;       }
;     }
;     if (kt + 2 < 128) {
;       const int kn = kt + 2;
; #pragma unroll
;       for (int i = 0; i < 2; ++i) kreg[i] = *(const u32x4*)(kbase + ((size_t)i * SEQ + kn * 64) * 64 + tid * 8);
; #pragma unroll
;       for (int i = 0; i < 2; ++i) {
;         const int cid = tid + NT * i;
;         const int e = cid >> 3, kc = cid & 7;
;         vreg[i] = *(const u32x4*)(vbase + (size_t)e * VTP + kn * 64 + kc * 8);
;       }
;     }
;     __builtin_amdgcn_sched_barrier(0x38F);
;     if (kt >= 0) {
;       const u16* Kc = Ks + (kt & 1) * (256 * 72);
;       const u16* Vc = Kc + 2 * 64 * 72;
;       bf16x8 kf[8];
; #pragma unroll
;       for (int i = 0; i < 8; ++i)
;         kf[i] = *(const bf16x8*)(Kc + (c * 64 + 32 * (i & 1) + li) * 72 + 16 * (i >> 1) + 8 * g);
;       u32x4 vf[16];
; #pragma unroll
;       for (int i = 0; i < 16; ++i) {
;         const int eb = i & 3, s = (i >> 2) & 1, kb = i >> 3;
;         vf[i] = *(const u32x4*)(Vc + (32 * eb + li) * 72 + 32 * kb + 16 * s + 8 * g);
;       }
;       f32x16 S[2];
; #pragma unroll
;       for (int kb = 0; kb < 2; ++kb)
; #pragma unroll
;         for (int r = 0; r < 16; ++r) S[kb][r] = negm;
; #pragma unroll
;       for (int i = 0; i < 8; ++i) S[i & 1] = MFMA(kf[i], qf[i >> 1], S[i & 1]);
;       u32x4 pk[4];
;       float sum = 0.f;
; #pragma unroll
;       for (int ch = 0; ch < 4; ++ch) {
;         const int kb = ch >> 1, s = ch & 1;
; #pragma unroll
;         for (int j2 = 0; j2 < 4; ++j2) {
;           const float p0 = __builtin_amdgcn_exp2f(S[kb][8 * s + 2 * j2]);
.Lat_exit:
	ds_read_b128 v[128:131], v150 offset:0
	ds_read_b128 v[132:135], v150 offset:32
	ds_read_b128 v[136:139], v150 offset:64
	ds_read_b128 v[152:155], v150 offset:96
	ds_read_b128 v[224:227], v150 offset:4608
	ds_read_b128 v[244:247], v150 offset:4640
	global_load_dwordx4 v[232:235], v148, s[98:99]
	global_load_dwordx4 v[228:231], v156, s[98:99]
	global_load_dwordx4 v[236:239], v146, s[100:101]
	global_load_dwordx4 v[240:243], v144, s[100:101]
	s_waitcnt lgkmcnt(4)
	v_mfma_f32_32x32x16_bf16 v[96:111], v[128:131], v[112:115], v[16:31]
	ds_read_b128 v[128:131], v150 offset:4672
	v_add_f32_e32 v167, v167, v88
	v_add_f32_e32 v190, v190, v89
	v_mfma_f32_32x32x16_bf16 v[96:111], v[132:135], v[116:119], v[96:111]
	ds_read_b128 v[132:135], v150 offset:4704
	v_add_f32_e32 v191, v191, v90
	v_add_f32_e32 v196, v196, v91
	s_waitcnt lgkmcnt(4)
	v_mfma_f32_32x32x16_bf16 v[96:111], v[136:139], v[124:127], v[96:111]
	ds_read_b128 v[136:139], v151 offset:0
	v_add_f32_e32 v167, v167, v92
	v_add_f32_e32 v190, v190, v93
	v_mfma_f32_32x32x16_bf16 v[96:111], v[152:155], v[120:123], v[96:111]
	ds_read_b128 v[152:155], v151 offset:4608
	v_add_f32_e32 v191, v191, v94
	v_add_f32_e32 v196, v196, v95
	s_add_u32 s98, s98, s14
	s_addc_u32 s99, s99, s15
	s_waitcnt lgkmcnt(4)
	v_mfma_f32_32x32x16_bf16 v[80:95], v[224:227], v[112:115], v[16:31]
	ds_read_b128 v[224:227], v151 offset:9216
	s_add_u32 s100, s100, s58
	s_addc_u32 s101, s101, s59
	v_mfma_f32_32x32x16_bf16 v[80:95], v[244:247], v[116:119], v[80:95]
	ds_read_b128 v[244:247], v151 offset:13824
	s_nop 2
	v_exp_f32_e32 v96, v96
	v_exp_f32_e32 v97, v97
	s_waitcnt lgkmcnt(4)
	v_mfma_f32_32x32x16_bf16 v[80:95], v[128:131], v[124:127], v[80:95]
	ds_read_b128 v[128:131], v151 offset:32
	v_exp_f32_e32 v98, v98
	v_exp_f32_e32 v99, v99
	v_exp_f32_e32 v100, v100
	v_mfma_f32_32x32x16_bf16 v[80:95], v[132:135], v[120:123], v[80:95]
	ds_read_b128 v[132:135], v151 offset:4640
	v_exp_f32_e32 v101, v101
	v_exp_f32_e32 v102, v102
	v_exp_f32_e32 v103, v103
	v_add_f32_e32 v167, v167, v96
	v_add_f32_e32 v190, v190, v97
	v_add_f32_e32 v191, v191, v98
	v_cvt_pk_bf16_f32 v176, v96, v97
	v_cvt_pk_bf16_f32 v177, v98, v99
	v_cvt_pk_bf16_f32 v178, v100, v101
	v_cvt_pk_bf16_f32 v179, v102, v103
	v_add_f32_e32 v196, v196, v99
	v_add_f32_e32 v167, v167, v100
	v_add_f32_e32 v190, v190, v101
	v_add_f32_e32 v191, v191, v102
	v_add_f32_e32 v196, v196, v103
	s_waitcnt lgkmcnt(4)
	v_mfma_f32_32x32x16_bf16 v[64:79], v[136:139], v[176:179], v[64:79]
	ds_read_b128 v[136:139], v151 offset:9248
	v_exp_f32_e32 v104, v104
	v_exp_f32_e32 v105, v105
	v_mfma_f32_32x32x16_bf16 v[48:63], v[152:155], v[176:179], v[48:63]
	ds_read_b128 v[152:155], v151 offset:13856
	v_exp_f32_e32 v106, v106
	v_exp_f32_e32 v107, v107
	v_cvt_pk_bf16_f32 v180, v104, v105
	s_waitcnt lgkmcnt(4)
	v_mfma_f32_32x32x16_bf16 v[32:47], v[224:227], v[176:179], v[32:47]
	ds_read_b128 v[224:227], v151 offset:64
	v_exp_f32_e32 v108, v108
	v_exp_f32_e32 v109, v109
	v_cvt_pk_bf16_f32 v181, v106, v107
	v_mfma_f32_32x32x16_bf16 v[0:15], v[244:247], v[176:179], v[0:15]
	ds_read_b128 v[244:247], v151 offset:4672
	v_exp_f32_e32 v110, v110
	v_exp_f32_e32 v111, v111
	v_cvt_pk_bf16_f32 v182, v108, v109
	v_cvt_pk_bf16_f32 v183, v110, v111
	v_exp_f32_e32 v80, v80
	s_waitcnt lgkmcnt(4)
	v_mfma_f32_32x32x16_bf16 v[64:79], v[128:131], v[180:183], v[64:79]
	ds_read_b128 v[128:131], v151 offset:9280
	v_exp_f32_e32 v81, v81
	v_mfma_f32_32x32x16_bf16 v[48:63], v[132:135], v[180:183], v[48:63]
	ds_read_b128 v[132:135], v151 offset:13888
	v_exp_f32_e32 v82, v82
	v_exp_f32_e32 v83, v83
	v_cvt_pk_bf16_f32 v184, v80, v81
	s_waitcnt lgkmcnt(4)
	v_mfma_f32_32x32x16_bf16 v[32:47], v[136:139], v[180:183], v[32:47]
	ds_read_b128 v[136:139], v151 offset:96
	v_exp_f32_e32 v84, v84
	v_exp_f32_e32 v85, v85
	v_cvt_pk_bf16_f32 v185, v82, v83
	v_mfma_f32_32x32x16_bf16 v[0:15], v[152:155], v[180:183], v[0:15]
	ds_read_b128 v[152:155], v151 offset:4704
	v_exp_f32_e32 v86, v86
	v_exp_f32_e32 v87, v87
	v_cvt_pk_bf16_f32 v186, v84, v85
	v_cvt_pk_bf16_f32 v187, v86, v87
	v_exp_f32_e32 v88, v88
	s_waitcnt lgkmcnt(4)
	v_mfma_f32_32x32x16_bf16 v[64:79], v[224:227], v[184:187], v[64:79]
	ds_read_b128 v[224:227], v151 offset:9312
	v_exp_f32_e32 v89, v89
	v_mfma_f32_32x32x16_bf16 v[48:63], v[244:247], v[184:187], v[48:63]
	ds_read_b128 v[244:247], v151 offset:13920
	v_exp_f32_e32 v90, v90
	v_exp_f32_e32 v91, v91
	v_cvt_pk_bf16_f32 v192, v88, v89
	s_waitcnt lgkmcnt(4)
	v_mfma_f32_32x32x16_bf16 v[32:47], v[128:131], v[184:187], v[32:47]
	v_exp_f32_e32 v92, v92
	v_exp_f32_e32 v93, v93
	v_cvt_pk_bf16_f32 v193, v90, v91
	s_waitcnt vmcnt(0)
	ds_write_b128 v168, v[228:231] offset:36864
	ds_write_b128 v168, v[232:235] offset:46080
	v_mfma_f32_32x32x16_bf16 v[0:15], v[132:135], v[184:187], v[0:15]
	v_exp_f32_e32 v94, v94
	v_exp_f32_e32 v95, v95
	v_cvt_pk_bf16_f32 v194, v92, v93
	v_cvt_pk_bf16_f32 v195, v94, v95
	v_add_f32_e32 v167, v167, v104
	ds_write_b64 v169, v[236:237] offset:55296
	ds_write_b64 v169, v[238:239] offset:55312
	s_waitcnt lgkmcnt(6)
	v_mfma_f32_32x32x16_bf16 v[64:79], v[136:139], v[192:195], v[64:79]
	v_add_f32_e32 v190, v190, v105
	v_add_f32_e32 v191, v191, v106
	v_add_f32_e32 v196, v196, v107
	ds_write_b64 v143, v[240:241] offset:55296
	ds_write_b64 v143, v[242:243] offset:55312
	v_mfma_f32_32x32x16_bf16 v[48:63], v[152:155], v[192:195], v[48:63]
	v_add_f32_e32 v167, v167, v108
	v_add_f32_e32 v190, v190, v109
	v_add_f32_e32 v191, v191, v110
	v_add_f32_e32 v196, v196, v111
	s_waitcnt lgkmcnt(6)
	v_mfma_f32_32x32x16_bf16 v[32:47], v[224:227], v[192:195], v[32:47]
	v_add_f32_e32 v167, v167, v80
	v_add_f32_e32 v190, v190, v81
	v_add_f32_e32 v191, v191, v82
	v_add_f32_e32 v196, v196, v83
	v_mfma_f32_32x32x16_bf16 v[0:15], v[244:247], v[192:195], v[0:15]
	v_add_f32_e32 v167, v167, v84
	v_add_f32_e32 v190, v190, v85
	v_add_f32_e32 v191, v191, v86
	v_add_f32_e32 v196, v196, v87
	s_waitcnt lgkmcnt(0)
	s_barrier
; DI void attn_item(const P& p, int l, int item, char* smem) {
;     ...
;   for (int kt = -1; kt < 128; ++kt) {
;     if (kt + 1 < 128) {
;       u16* Kd = Ks + ((kt + 1) & 1) * (256 * 72);
;       u16* Vd = Kd + 2 * 64 * 72;
; #pragma unroll
;       for (int i = 0; i < 2; ++i) {
;         const int row = tid >> 3, kc = tid & 7;
;         *(u32x4*)(Kd + (i * 64 + row) * 72 + kc * 8) = kreg[i];
;       }
; #pragma unroll
;       for (int i = 0; i < 2; ++i) {
;         const int cid = tid + NT * i;
;         const int e = cid >> 3, kc = cid & 7;
;         uint2 w0; w0.x = vreg[i][0]; w0.y = vreg[i][1];
;         uint2 w1; w1.x = vreg[i][2]; w1.y = vreg[i][3];
;         u16* vd = Vd + e * 72 + (kc >> 1) * 16 + (kc & 1) * 4;
;         *(uint2*)vd = w0;
;         *(uint2*)(vd + 8) = w1;
;       }
;     }
;     if (kt + 2 < 128) {
;       const int kn = kt + 2;
; #pragma unroll
;       for (int i = 0; i < 2; ++i) kreg[i] = *(const u32x4*)(kbase + ((size_t)i * SEQ + kn * 64) * 64 + tid * 8);
; #pragma unroll
;       for (int i = 0; i < 2; ++i) {
;         const int cid = tid + NT * i;
;         const int e = cid >> 3, kc = cid & 7;
;         vreg[i] = *(const u32x4*)(vbase + (size_t)e * VTP + kn * 64 + kc * 8);
;       }
;     }
;     __builtin_amdgcn_sched_barrier(0x38F);
;     if (kt >= 0) {
;       const u16* Kc = Ks + (kt & 1) * (256 * 72);
;       const u16* Vc = Kc + 2 * 64 * 72;
;       bf16x8 kf[8];
; #pragma unroll
;       for (int i = 0; i < 8; ++i)
;         kf[i] = *(const bf16x8*)(Kc + (c * 64 + 32 * (i & 1) + li) * 72 + 16 * (i >> 1) + 8 * g);
;       u32x4 vf[16];
; #pragma unroll
;       for (int i = 0; i < 16; ++i) {
;         const int eb = i & 3, s = (i >> 2) & 1, kb = i >> 3;
;         vf[i] = *(const u32x4*)(Vc + (32 * eb + li) * 72 + 32 * kb + 16 * s + 8 * g);
;       }
;       f32x16 S[2];
; #pragma unroll
;       for (int kb = 0; kb < 2; ++kb)
; #pragma unroll
;         for (int r = 0; r < 16; ++r) S[kb][r] = negm;
; #pragma unroll
;       for (int i = 0; i < 8; ++i) S[i & 1] = MFMA(kf[i], qf[i >> 1], S[i & 1]);
;       u32x4 pk[4];
;       float sum = 0.f;
; #pragma unroll
;       for (int ch = 0; ch < 4; ++ch) {
;         const int kb = ch >> 1, s = ch & 1;
; #pragma unroll
;         for (int j2 = 0; j2 < 4; ++j2) {
;           const float p0 = __builtin_amdgcn_exp2f(S[kb][8 * s + 2 * j2]);
	ds_read_b128 v[128:131], v150 offset:36864
	ds_read_b128 v[132:135], v150 offset:36896
	ds_read_b128 v[136:139], v150 offset:36928
	ds_read_b128 v[152:155], v150 offset:36960
	ds_read_b128 v[224:227], v150 offset:41472
	ds_read_b128 v[244:247], v150 offset:41504
	s_waitcnt lgkmcnt(4)
	v_mfma_f32_32x32x16_bf16 v[96:111], v[128:131], v[112:115], v[16:31]
	ds_read_b128 v[128:131], v150 offset:41536
	v_add_f32_e32 v167, v167, v88
	v_add_f32_e32 v190, v190, v89
	v_mfma_f32_32x32x16_bf16 v[96:111], v[132:135], v[116:119], v[96:111]
	ds_read_b128 v[132:135], v150 offset:41568
	v_add_f32_e32 v191, v191, v90
	v_add_f32_e32 v196, v196, v91
	s_waitcnt lgkmcnt(4)
	v_mfma_f32_32x32x16_bf16 v[96:111], v[136:139], v[124:127], v[96:111]
	ds_read_b128 v[136:139], v151 offset:36864
	v_add_f32_e32 v167, v167, v92
	v_add_f32_e32 v190, v190, v93
	v_mfma_f32_32x32x16_bf16 v[96:111], v[152:155], v[120:123], v[96:111]
	ds_read_b128 v[152:155], v151 offset:41472
	v_add_f32_e32 v191, v191, v94
	v_add_f32_e32 v196, v196, v95
	s_waitcnt lgkmcnt(4)
	v_mfma_f32_32x32x16_bf16 v[80:95], v[224:227], v[112:115], v[16:31]
	ds_read_b128 v[224:227], v151 offset:46080
	v_mfma_f32_32x32x16_bf16 v[80:95], v[244:247], v[116:119], v[80:95]
	ds_read_b128 v[244:247], v151 offset:50688
	s_nop 6
	v_exp_f32_e32 v96, v96
	v_exp_f32_e32 v97, v97
	s_waitcnt lgkmcnt(4)
	v_mfma_f32_32x32x16_bf16 v[80:95], v[128:131], v[124:127], v[80:95]
	ds_read_b128 v[128:131], v151 offset:36896
	v_exp_f32_e32 v98, v98
	v_exp_f32_e32 v99, v99
	v_exp_f32_e32 v100, v100
	v_mfma_f32_32x32x16_bf16 v[80:95], v[132:135], v[120:123], v[80:95]
	ds_read_b128 v[132:135], v151 offset:41504
	v_exp_f32_e32 v101, v101
	v_exp_f32_e32 v102, v102
	v_exp_f32_e32 v103, v103
	v_add_f32_e32 v167, v167, v96
	v_add_f32_e32 v190, v190, v97
	v_add_f32_e32 v191, v191, v98
	v_cvt_pk_bf16_f32 v176, v96, v97
	v_cvt_pk_bf16_f32 v177, v98, v99
	v_cvt_pk_bf16_f32 v178, v100, v101
	v_cvt_pk_bf16_f32 v179, v102, v103
	v_add_f32_e32 v196, v196, v99
	v_add_f32_e32 v167, v167, v100
	v_add_f32_e32 v190, v190, v101
	v_add_f32_e32 v191, v191, v102
	v_add_f32_e32 v196, v196, v103
	s_waitcnt lgkmcnt(4)
	v_mfma_f32_32x32x16_bf16 v[64:79], v[136:139], v[176:179], v[64:79]
	ds_read_b128 v[136:139], v151 offset:46112
	v_exp_f32_e32 v104, v104
	v_exp_f32_e32 v105, v105
	v_mfma_f32_32x32x16_bf16 v[48:63], v[152:155], v[176:179], v[48:63]
	ds_read_b128 v[152:155], v151 offset:50720
	v_exp_f32_e32 v106, v106
	v_exp_f32_e32 v107, v107
	v_cvt_pk_bf16_f32 v180, v104, v105
	s_waitcnt lgkmcnt(4)
	v_mfma_f32_32x32x16_bf16 v[32:47], v[224:227], v[176:179], v[32:47]
	ds_read_b128 v[224:227], v151 offset:36928
	v_exp_f32_e32 v108, v108
	v_exp_f32_e32 v109, v109
	v_cvt_pk_bf16_f32 v181, v106, v107
	v_mfma_f32_32x32x16_bf16 v[0:15], v[244:247], v[176:179], v[0:15]
	ds_read_b128 v[244:247], v151 offset:41536
	v_exp_f32_e32 v110, v110
	v_exp_f32_e32 v111, v111
	v_cvt_pk_bf16_f32 v182, v108, v109
	v_cvt_pk_bf16_f32 v183, v110, v111
	v_exp_f32_e32 v80, v80
	s_waitcnt lgkmcnt(4)
	v_mfma_f32_32x32x16_bf16 v[64:79], v[128:131], v[180:183], v[64:79]
	ds_read_b128 v[128:131], v151 offset:46144
	v_exp_f32_e32 v81, v81
	v_mfma_f32_32x32x16_bf16 v[48:63], v[132:135], v[180:183], v[48:63]
	ds_read_b128 v[132:135], v151 offset:50752
	v_exp_f32_e32 v82, v82
	v_exp_f32_e32 v83, v83
	v_cvt_pk_bf16_f32 v184, v80, v81
	s_waitcnt lgkmcnt(4)
	v_mfma_f32_32x32x16_bf16 v[32:47], v[136:139], v[180:183], v[32:47]
	ds_read_b128 v[136:139], v151 offset:36960
	v_exp_f32_e32 v84, v84
	v_exp_f32_e32 v85, v85
	v_cvt_pk_bf16_f32 v185, v82, v83
	v_mfma_f32_32x32x16_bf16 v[0:15], v[152:155], v[180:183], v[0:15]
	ds_read_b128 v[152:155], v151 offset:41568
	v_exp_f32_e32 v86, v86
	v_exp_f32_e32 v87, v87
	v_cvt_pk_bf16_f32 v186, v84, v85
	v_cvt_pk_bf16_f32 v187, v86, v87
	v_exp_f32_e32 v88, v88
	s_waitcnt lgkmcnt(4)
	v_mfma_f32_32x32x16_bf16 v[64:79], v[224:227], v[184:187], v[64:79]
	ds_read_b128 v[224:227], v151 offset:46176
	v_exp_f32_e32 v89, v89
	v_mfma_f32_32x32x16_bf16 v[48:63], v[244:247], v[184:187], v[48:63]
	ds_read_b128 v[244:247], v151 offset:50784
	v_exp_f32_e32 v90, v90
	v_exp_f32_e32 v91, v91
	v_cvt_pk_bf16_f32 v192, v88, v89
	s_waitcnt lgkmcnt(4)
	v_mfma_f32_32x32x16_bf16 v[32:47], v[128:131], v[184:187], v[32:47]
	v_exp_f32_e32 v92, v92
	v_exp_f32_e32 v93, v93
	v_cvt_pk_bf16_f32 v193, v90, v91
	v_mfma_f32_32x32x16_bf16 v[0:15], v[132:135], v[184:187], v[0:15]
	v_exp_f32_e32 v94, v94
	v_exp_f32_e32 v95, v95
	v_cvt_pk_bf16_f32 v194, v92, v93
	v_cvt_pk_bf16_f32 v195, v94, v95
	v_add_f32_e32 v167, v167, v104
	s_waitcnt lgkmcnt(2)
	v_mfma_f32_32x32x16_bf16 v[64:79], v[136:139], v[192:195], v[64:79]
	v_add_f32_e32 v190, v190, v105
	v_add_f32_e32 v191, v191, v106
	v_add_f32_e32 v196, v196, v107
	v_mfma_f32_32x32x16_bf16 v[48:63], v[152:155], v[192:195], v[48:63]
	v_add_f32_e32 v167, v167, v108
	v_add_f32_e32 v190, v190, v109
	v_add_f32_e32 v191, v191, v110
	v_add_f32_e32 v196, v196, v111
	s_waitcnt lgkmcnt(0)
	v_mfma_f32_32x32x16_bf16 v[32:47], v[224:227], v[192:195], v[32:47]
	v_add_f32_e32 v167, v167, v80
	v_add_f32_e32 v190, v190, v81
	v_add_f32_e32 v191, v191, v82
	v_add_f32_e32 v196, v196, v83
	v_mfma_f32_32x32x16_bf16 v[0:15], v[244:247], v[192:195], v[0:15]
	v_add_f32_e32 v167, v167, v84
	v_add_f32_e32 v190, v190, v85
	v_add_f32_e32 v191, v191, v86
	v_add_f32_e32 v196, v196, v87
	s_waitcnt lgkmcnt(0)
	s_barrier
; DI void attn_item(const P& p, int l, int item, char* smem) {
;     ...
;     lam = __expf(s1) - __expf(s2) + lam_init;
;     ...
;   const float lt = ls + __shfl_xor(ls, 32);
;   const float inv = (c == 0) ? (1.0f / lt) : (lam / lt);
;   float* exch = (float*)smem + qg * (64 * 64);
;   if (c == 1) {
; #pragma unroll
;     for (int eb = 0; eb < 4; ++eb)
; #pragma unroll
;       for (int r = 0; r < 16; ++r) exch[(eb * 16 + r) * 64 + lane] = O[eb][r] * inv;
;   }
;   __syncthreads();
;   if (c == 0) {
;     float ss = 0.f;
; #pragma unroll
;     for (int eb = 0; eb < 4; ++eb)
; #pragma unroll
;       for (int r = 0; r < 16; ++r) {
;         const float o = O[eb][r] * inv - exch[(eb * 16 + r) * 64 + lane];
;         O[eb][r] = o;
;         ss += o * o;
;       }
;     ss += __shfl_xor(ss, 32);
;     const float rn = rsqrtf(ss * (1.0f / 128.0f) + 1e-5f) * (1.0f - lam_init);
;     const size_t tok = (size_t)b * SEQ + tq;
; #pragma unroll
;     for (int eb = 0; eb < 4; ++eb)
; #pragma unroll
;       for (int rq = 0; rq < 4; ++rq) {
;         const int e = 32 * eb + 8 * rq + 4 * g;
;         const uint2 gt = *(const uint2*)(p.AG + tok * 512 + h * 128 + e);
;         const float4 sg = *(const float4*)(p.subg + l * 128 + e);
	v_add_f32_e32 v167, v167, v88
	v_add_f32_e32 v190, v190, v89
	v_add_f32_e32 v191, v191, v90
	v_add_f32_e32 v196, v196, v91
	v_add_f32_e32 v167, v167, v92
	v_add_f32_e32 v190, v190, v93
	v_add_f32_e32 v191, v191, v94
	v_add_f32_e32 v196, v196, v95
	v_add_f32_e32 v167, v167, v190
	v_add_f32_e32 v191, v191, v196
	v_readlane_b32 s6, v248, 5
	v_add_f32_e32 v96, v165, v166
	v_add_f32_e32 v97, v163, v164
	v_mul_f32_e32 v96, 0x3fb8aa3b, v96
	v_mul_f32_e32 v97, 0x3fb8aa3b, v97
	v_exp_f32_e32 v139, v96
	v_exp_f32_e32 v17, v97
	v_add_f32_e32 v16, v167, v191
	ds_bpermute_b32 v18, v158, v16
	v_sub_f32_e32 v17, v17, v139
	v_add_f32_e32 v17, s6, v17
	s_movk_i32 s6, 0x100
	v_cmp_gt_u32_e64 s[6:7], s6, v161
	s_waitcnt lgkmcnt(0)
	v_add_f32_e32 v16, v16, v18
	s_nop 0
	v_cndmask_b32_e64 v17, v17, 1.0, s[6:7]
	v_div_scale_f32 v18, s[10:11], v16, v16, v17
	v_rcp_f32_e32 v19, v18
	s_nop 0
	v_fma_f32 v24, -v18, v19, 1.0
	s_nop 0
	v_fmac_f32_e32 v19, v24, v19
	v_div_scale_f32 v24, vcc, v17, v16, v17
	v_mul_f32_e32 v25, v24, v19
	v_fma_f32 v26, -v18, v25, v24
	v_fmac_f32_e32 v25, v26, v19
	v_fma_f32 v18, -v18, v25, v24
	s_nop 0
	v_div_fmas_f32 v18, v18, v19, v25
	v_div_fixup_f32 v80, v18, v16, v17
	v_lshl_add_u32 v16, v162, 14, 0
	v_cmp_eq_u32_e32 vcc, 1, v160
	v_lshl_add_u32 v18, v141, 2, v16
	s_nop 0
	s_and_saveexec_b64 s[10:11], s[6:7]
	s_cbranch_execz .Lfin_nl
	v_and_b32_e32 v142, 15, v161
	v_bfe_u32 v143, v161, 4, 2
	v_and_b32_e32 v144, 0xffffffe0, v140
	v_add_u32_e32 v144, v144, v143
	s_lshl_b32 s56, s12, 11
	s_and_b32 s56, s56, 0x2000
	v_add_u32_e32 v144, s56, v144
	v_lshlrev_b32_e32 v144, 10, v144
	s_lshl_b32 s56, s95, 8
	s_and_b32 s56, s56, 0x300
	v_add_u32_e32 v144, s56, v144
	v_lshl_add_u32 v144, v142, 4, v144
	v_mov_b32_e32 v147, v144
	v_lshlrev_b32_e32 v145, 5, v142
	global_load_dwordx4 v[100:103], v145, s[30:31]
	global_load_dwordx4 v[104:107], v145, s[30:31] offset:16
	global_load_dwordx4 v[228:231], v144, s[44:45]
	v_add_u32_e32 v144, 0x1000, v144
	global_load_dwordx4 v[232:235], v144, s[44:45]
	v_add_u32_e32 v144, 0x1000, v144
	global_load_dwordx4 v[236:239], v144, s[44:45]
	v_add_u32_e32 v144, 0x1000, v144
	global_load_dwordx4 v[240:243], v144, s[44:45]
	v_add_u32_e32 v144, 0x1000, v144
	global_load_dwordx4 v[84:87], v144, s[44:45]
	v_add_u32_e32 v144, 0x1000, v144
	global_load_dwordx4 v[88:91], v144, s[44:45]
	v_add_u32_e32 v144, 0x1000, v144
	global_load_dwordx4 v[92:95], v144, s[44:45]
	v_add_u32_e32 v144, 0x1000, v144
	global_load_dwordx4 v[96:99], v144, s[44:45]
